# final rmsnorm pass writes y with the nt hint (never re-read) so x3 stays in the memory-side cache until read
# baseline (speedup 1.0000x reference)
; __global__ void __launch_bounds__(NTHREADS, 2) fwd_megakernel(Args args) {
;     ...
;         for (int row = gw; row < T; row += NGW) {
;             f32x4* xr = X4 + (size_t)row * (D / 4) + lane;
;             const float r = __builtin_amdgcn_rsqf(ss3[row] * (1.0f / D) + EPS);
;             f32x4 v[8];
; #pragma unroll
;             for (int j = 0; j < 8; ++j) v[j] = xr[64 * j];
; #pragma unroll
;             for (int j = 0; j < 8; ++j) xr[64 * j] = v[j] * r * gf[lane + 64 * j];
;         }
.LBB0_1505:
	global_load_dwordx4 v[32:35], v[2:3], off
	global_load_dwordx4 v[36:39], v[2:3], off offset:1024
	global_load_dwordx4 v[40:43], v[2:3], off offset:2048
	global_load_dwordx4 v[44:47], v[2:3], off offset:3072
	global_load_dwordx4 v[48:51], v[4:5], off
	global_load_dwordx4 v[52:55], v[6:7], off
	global_load_dwordx4 v[56:59], v[8:9], off
	global_load_dwordx4 v[60:63], v[10:11], off
	v_add_co_u32_e32 v14, vcc, 0xfffff400, v12
	s_nop 1
	v_addc_co_u32_e32 v15, vcc, -1, v13, vcc
	global_load_dword v28, v1, s[0:1]
	s_add_u32 s0, s0, s2
	s_addc_u32 s1, s1, s3
	global_load_dwordx4 v[64:67], v[14:15], off offset:-4096
	global_load_dwordx4 v[68:71], v[14:15], off offset:-3072
	global_load_dwordx4 v[72:75], v[14:15], off offset:-2048
	global_load_dwordx4 v[76:79], v[14:15], off offset:-1024
	global_load_dwordx4 v[80:83], v[14:15], off offset:0
	global_load_dwordx4 v[84:87], v[14:15], off offset:1024
	global_load_dwordx4 v[88:91], v[14:15], off offset:2048
	global_load_dwordx4 v[92:95], v[14:15], off offset:3072
	s_add_i32 s6, s6, s24
	s_cmpk_gt_i32 s6, 0x47ff
	s_cbranch_scc1 .Lp8_tail_a
	v_lshl_add_u64 v[16:17], v[14:15], 0, s[4:5]
	global_load_dword v30, v1, s[0:1]
	s_add_u32 s0, s0, s2
	s_addc_u32 s1, s1, s3
	global_load_dwordx4 v[96:99], v[16:17], off offset:-4096
	global_load_dwordx4 v[100:103], v[16:17], off offset:-3072
	global_load_dwordx4 v[104:107], v[16:17], off offset:-2048
	global_load_dwordx4 v[108:111], v[16:17], off offset:-1024
	global_load_dwordx4 v[112:115], v[16:17], off offset:0
	global_load_dwordx4 v[116:119], v[16:17], off offset:1024
	global_load_dwordx4 v[120:123], v[16:17], off offset:2048
	global_load_dwordx4 v[124:127], v[16:17], off offset:3072
	s_waitcnt vmcnt(9)
	v_fmamk_f32 v28, v28, 0x3a000000, v0
	v_rsq_f32_e32 v28, v28
	s_nop 0
	v_mul_f32_e32 v64, v28, v64
	v_mul_f32_e32 v65, v28, v65
	v_mul_f32_e32 v66, v28, v66
	v_mul_f32_e32 v67, v28, v67
	v_mul_f32_e32 v64, v64, v32
	v_mul_f32_e32 v65, v65, v33
	v_mul_f32_e32 v66, v66, v34
	v_mul_f32_e32 v67, v67, v35
	global_store_dwordx4 v[14:15], v[64:67], off offset:-4096 nt
	v_mul_f32_e32 v68, v28, v68
	v_mul_f32_e32 v69, v28, v69
	v_mul_f32_e32 v70, v28, v70
	v_mul_f32_e32 v71, v28, v71
	v_mul_f32_e32 v68, v68, v36
	v_mul_f32_e32 v69, v69, v37
	v_mul_f32_e32 v70, v70, v38
	v_mul_f32_e32 v71, v71, v39
	global_store_dwordx4 v[14:15], v[68:71], off offset:-3072 nt
	v_mul_f32_e32 v72, v28, v72
	v_mul_f32_e32 v73, v28, v73
	v_mul_f32_e32 v74, v28, v74
	v_mul_f32_e32 v75, v28, v75
	v_mul_f32_e32 v72, v72, v40
	v_mul_f32_e32 v73, v73, v41
	v_mul_f32_e32 v74, v74, v42
	v_mul_f32_e32 v75, v75, v43
	global_store_dwordx4 v[14:15], v[72:75], off offset:-2048 nt
	v_mul_f32_e32 v76, v28, v76
	v_mul_f32_e32 v77, v28, v77
	v_mul_f32_e32 v78, v28, v78
	v_mul_f32_e32 v79, v28, v79
	v_mul_f32_e32 v76, v76, v44
	v_mul_f32_e32 v77, v77, v45
	v_mul_f32_e32 v78, v78, v46
	v_mul_f32_e32 v79, v79, v47
	global_store_dwordx4 v[14:15], v[76:79], off offset:-1024 nt
	v_mul_f32_e32 v80, v28, v80
	v_mul_f32_e32 v81, v28, v81
	v_mul_f32_e32 v82, v28, v82
	v_mul_f32_e32 v83, v28, v83
	v_mul_f32_e32 v80, v80, v48
	v_mul_f32_e32 v81, v81, v49
	v_mul_f32_e32 v82, v82, v50
	v_mul_f32_e32 v83, v83, v51
	global_store_dwordx4 v[14:15], v[80:83], off offset:0 nt
	v_mul_f32_e32 v84, v28, v84
	v_mul_f32_e32 v85, v28, v85
	v_mul_f32_e32 v86, v28, v86
	v_mul_f32_e32 v87, v28, v87
	v_mul_f32_e32 v84, v84, v52
	v_mul_f32_e32 v85, v85, v53
	v_mul_f32_e32 v86, v86, v54
	v_mul_f32_e32 v87, v87, v55
	global_store_dwordx4 v[14:15], v[84:87], off offset:1024 nt
	v_mul_f32_e32 v88, v28, v88
	v_mul_f32_e32 v89, v28, v89
	v_mul_f32_e32 v90, v28, v90
	v_mul_f32_e32 v91, v28, v91
	v_mul_f32_e32 v88, v88, v56
	v_mul_f32_e32 v89, v89, v57
	v_mul_f32_e32 v90, v90, v58
	v_mul_f32_e32 v91, v91, v59
	global_store_dwordx4 v[14:15], v[88:91], off offset:2048 nt
	v_mul_f32_e32 v92, v28, v92
	v_mul_f32_e32 v93, v28, v93
	v_mul_f32_e32 v94, v28, v94
	v_mul_f32_e32 v95, v28, v95
	v_mul_f32_e32 v92, v92, v60
	v_mul_f32_e32 v93, v93, v61
	v_mul_f32_e32 v94, v94, v62
	v_mul_f32_e32 v95, v95, v63
	global_store_dwordx4 v[14:15], v[92:95], off offset:3072 nt
.Lp8_loop:
	s_add_i32 s6, s6, s24
	s_cmpk_gt_i32 s6, 0x47ff
	s_cbranch_scc1 .Lp8_tail_b
	v_lshl_add_u64 v[14:15], v[16:17], 0, s[4:5]
	global_load_dword v28, v1, s[0:1]
	s_add_u32 s0, s0, s2
	s_addc_u32 s1, s1, s3
	global_load_dwordx4 v[64:67], v[14:15], off offset:-4096
	global_load_dwordx4 v[68:71], v[14:15], off offset:-3072
	global_load_dwordx4 v[72:75], v[14:15], off offset:-2048
	global_load_dwordx4 v[76:79], v[14:15], off offset:-1024
	global_load_dwordx4 v[80:83], v[14:15], off offset:0
	global_load_dwordx4 v[84:87], v[14:15], off offset:1024
	global_load_dwordx4 v[88:91], v[14:15], off offset:2048
	global_load_dwordx4 v[92:95], v[14:15], off offset:3072
	s_waitcnt vmcnt(17)
; __global__ void __launch_bounds__(NTHREADS, 2) fwd_megakernel(Args args) {
;     ...
;         for (int row = gw; row < T; row += NGW) {
;             f32x4* xr = X4 + (size_t)row * (D / 4) + lane;
;             const float r = __builtin_amdgcn_rsqf(ss3[row] * (1.0f / D) + EPS);
;             f32x4 v[8];
; #pragma unroll
;             for (int j = 0; j < 8; ++j) v[j] = xr[64 * j];
; #pragma unroll
;             for (int j = 0; j < 8; ++j) xr[64 * j] = v[j] * r * gf[lane + 64 * j];
;         }
	v_fmamk_f32 v30, v30, 0x3a000000, v0
	v_rsq_f32_e32 v30, v30
	s_nop 0
	v_mul_f32_e32 v96, v30, v96
	v_mul_f32_e32 v97, v30, v97
	v_mul_f32_e32 v98, v30, v98
	v_mul_f32_e32 v99, v30, v99
	v_mul_f32_e32 v96, v96, v32
	v_mul_f32_e32 v97, v97, v33
	v_mul_f32_e32 v98, v98, v34
	v_mul_f32_e32 v99, v99, v35
	global_store_dwordx4 v[16:17], v[96:99], off offset:-4096 nt
	v_mul_f32_e32 v100, v30, v100
	v_mul_f32_e32 v101, v30, v101
	v_mul_f32_e32 v102, v30, v102
	v_mul_f32_e32 v103, v30, v103
	v_mul_f32_e32 v100, v100, v36
	v_mul_f32_e32 v101, v101, v37
	v_mul_f32_e32 v102, v102, v38
	v_mul_f32_e32 v103, v103, v39
	global_store_dwordx4 v[16:17], v[100:103], off offset:-3072 nt
	v_mul_f32_e32 v104, v30, v104
	v_mul_f32_e32 v105, v30, v105
	v_mul_f32_e32 v106, v30, v106
	v_mul_f32_e32 v107, v30, v107
	v_mul_f32_e32 v104, v104, v40
	v_mul_f32_e32 v105, v105, v41
	v_mul_f32_e32 v106, v106, v42
	v_mul_f32_e32 v107, v107, v43
	global_store_dwordx4 v[16:17], v[104:107], off offset:-2048 nt
	v_mul_f32_e32 v108, v30, v108
	v_mul_f32_e32 v109, v30, v109
	v_mul_f32_e32 v110, v30, v110
	v_mul_f32_e32 v111, v30, v111
	v_mul_f32_e32 v108, v108, v44
	v_mul_f32_e32 v109, v109, v45
	v_mul_f32_e32 v110, v110, v46
	v_mul_f32_e32 v111, v111, v47
	global_store_dwordx4 v[16:17], v[108:111], off offset:-1024 nt
	v_mul_f32_e32 v112, v30, v112
	v_mul_f32_e32 v113, v30, v113
	v_mul_f32_e32 v114, v30, v114
	v_mul_f32_e32 v115, v30, v115
	v_mul_f32_e32 v112, v112, v48
	v_mul_f32_e32 v113, v113, v49
	v_mul_f32_e32 v114, v114, v50
	v_mul_f32_e32 v115, v115, v51
	global_store_dwordx4 v[16:17], v[112:115], off offset:0 nt
	v_mul_f32_e32 v116, v30, v116
	v_mul_f32_e32 v117, v30, v117
	v_mul_f32_e32 v118, v30, v118
	v_mul_f32_e32 v119, v30, v119
	v_mul_f32_e32 v116, v116, v52
	v_mul_f32_e32 v117, v117, v53
	v_mul_f32_e32 v118, v118, v54
	v_mul_f32_e32 v119, v119, v55
	global_store_dwordx4 v[16:17], v[116:119], off offset:1024 nt
	v_mul_f32_e32 v120, v30, v120
	v_mul_f32_e32 v121, v30, v121
	v_mul_f32_e32 v122, v30, v122
	v_mul_f32_e32 v123, v30, v123
	v_mul_f32_e32 v120, v120, v56
	v_mul_f32_e32 v121, v121, v57
	v_mul_f32_e32 v122, v122, v58
	v_mul_f32_e32 v123, v123, v59
	global_store_dwordx4 v[16:17], v[120:123], off offset:2048 nt
	v_mul_f32_e32 v124, v30, v124
	v_mul_f32_e32 v125, v30, v125
	v_mul_f32_e32 v126, v30, v126
	v_mul_f32_e32 v127, v30, v127
	v_mul_f32_e32 v124, v124, v60
	v_mul_f32_e32 v125, v125, v61
	v_mul_f32_e32 v126, v126, v62
	v_mul_f32_e32 v127, v127, v63
	global_store_dwordx4 v[16:17], v[124:127], off offset:3072 nt
	s_add_i32 s6, s6, s24
	s_cmpk_gt_i32 s6, 0x47ff
	s_cbranch_scc1 .Lp8_tail_a
	v_lshl_add_u64 v[16:17], v[14:15], 0, s[4:5]
	global_load_dword v30, v1, s[0:1]
	s_add_u32 s0, s0, s2
	s_addc_u32 s1, s1, s3
	global_load_dwordx4 v[96:99], v[16:17], off offset:-4096
	global_load_dwordx4 v[100:103], v[16:17], off offset:-3072
	global_load_dwordx4 v[104:107], v[16:17], off offset:-2048
	global_load_dwordx4 v[108:111], v[16:17], off offset:-1024
	global_load_dwordx4 v[112:115], v[16:17], off offset:0
	global_load_dwordx4 v[116:119], v[16:17], off offset:1024
	global_load_dwordx4 v[120:123], v[16:17], off offset:2048
	global_load_dwordx4 v[124:127], v[16:17], off offset:3072
	s_waitcnt vmcnt(17)
	v_fmamk_f32 v28, v28, 0x3a000000, v0
	v_rsq_f32_e32 v28, v28
	s_nop 0
	v_mul_f32_e32 v64, v28, v64
	v_mul_f32_e32 v65, v28, v65
	v_mul_f32_e32 v66, v28, v66
	v_mul_f32_e32 v67, v28, v67
	v_mul_f32_e32 v64, v64, v32
	v_mul_f32_e32 v65, v65, v33
	v_mul_f32_e32 v66, v66, v34
	v_mul_f32_e32 v67, v67, v35
	global_store_dwordx4 v[14:15], v[64:67], off offset:-4096 nt
	v_mul_f32_e32 v68, v28, v68
	v_mul_f32_e32 v69, v28, v69
	v_mul_f32_e32 v70, v28, v70
	v_mul_f32_e32 v71, v28, v71
	v_mul_f32_e32 v68, v68, v36
	v_mul_f32_e32 v69, v69, v37
	v_mul_f32_e32 v70, v70, v38
	v_mul_f32_e32 v71, v71, v39
	global_store_dwordx4 v[14:15], v[68:71], off offset:-3072 nt
	v_mul_f32_e32 v72, v28, v72
	v_mul_f32_e32 v73, v28, v73
	v_mul_f32_e32 v74, v28, v74
	v_mul_f32_e32 v75, v28, v75
	v_mul_f32_e32 v72, v72, v40
	v_mul_f32_e32 v73, v73, v41
	v_mul_f32_e32 v74, v74, v42
	v_mul_f32_e32 v75, v75, v43
	global_store_dwordx4 v[14:15], v[72:75], off offset:-2048 nt
	v_mul_f32_e32 v76, v28, v76
	v_mul_f32_e32 v77, v28, v77
	v_mul_f32_e32 v78, v28, v78
	v_mul_f32_e32 v79, v28, v79
	v_mul_f32_e32 v76, v76, v44
	v_mul_f32_e32 v77, v77, v45
	v_mul_f32_e32 v78, v78, v46
	v_mul_f32_e32 v79, v79, v47
	global_store_dwordx4 v[14:15], v[76:79], off offset:-1024 nt
	v_mul_f32_e32 v80, v28, v80
	v_mul_f32_e32 v81, v28, v81
	v_mul_f32_e32 v82, v28, v82
	v_mul_f32_e32 v83, v28, v83
	v_mul_f32_e32 v80, v80, v48
	v_mul_f32_e32 v81, v81, v49
	v_mul_f32_e32 v82, v82, v50
	v_mul_f32_e32 v83, v83, v51
	global_store_dwordx4 v[14:15], v[80:83], off offset:0 nt
	v_mul_f32_e32 v84, v28, v84
	v_mul_f32_e32 v85, v28, v85
	v_mul_f32_e32 v86, v28, v86
	v_mul_f32_e32 v87, v28, v87
	v_mul_f32_e32 v84, v84, v52
	v_mul_f32_e32 v85, v85, v53
	v_mul_f32_e32 v86, v86, v54
	v_mul_f32_e32 v87, v87, v55
	global_store_dwordx4 v[14:15], v[84:87], off offset:1024 nt
	v_mul_f32_e32 v88, v28, v88
	v_mul_f32_e32 v89, v28, v89
	v_mul_f32_e32 v90, v28, v90
	v_mul_f32_e32 v91, v28, v91
	v_mul_f32_e32 v88, v88, v56
	v_mul_f32_e32 v89, v89, v57
	v_mul_f32_e32 v90, v90, v58
	v_mul_f32_e32 v91, v91, v59
	global_store_dwordx4 v[14:15], v[88:91], off offset:2048 nt
	v_mul_f32_e32 v92, v28, v92
	v_mul_f32_e32 v93, v28, v93
	v_mul_f32_e32 v94, v28, v94
	v_mul_f32_e32 v95, v28, v95
	v_mul_f32_e32 v92, v92, v60
	v_mul_f32_e32 v93, v93, v61
	v_mul_f32_e32 v94, v94, v62
	v_mul_f32_e32 v95, v95, v63
	global_store_dwordx4 v[14:15], v[92:95], off offset:3072 nt
	s_branch .Lp8_loop
; __global__ void __launch_bounds__(NTHREADS, 2) fwd_megakernel(Args args) {
;     ...
;         for (int row = gw; row < T; row += NGW) {
;             f32x4* xr = X4 + (size_t)row * (D / 4) + lane;
;             const float r = __builtin_amdgcn_rsqf(ss3[row] * (1.0f / D) + EPS);
;             f32x4 v[8];
; #pragma unroll
;             for (int j = 0; j < 8; ++j) v[j] = xr[64 * j];
; #pragma unroll
;             for (int j = 0; j < 8; ++j) xr[64 * j] = v[j] * r * gf[lane + 64 * j];
;         }
.Lp8_tail_a:
	s_waitcnt vmcnt(0)
	v_fmamk_f32 v28, v28, 0x3a000000, v0
	v_rsq_f32_e32 v28, v28
	s_nop 0
	v_mul_f32_e32 v64, v28, v64
	v_mul_f32_e32 v65, v28, v65
	v_mul_f32_e32 v66, v28, v66
	v_mul_f32_e32 v67, v28, v67
	v_mul_f32_e32 v64, v64, v32
	v_mul_f32_e32 v65, v65, v33
	v_mul_f32_e32 v66, v66, v34
	v_mul_f32_e32 v67, v67, v35
	global_store_dwordx4 v[14:15], v[64:67], off offset:-4096 nt
	v_mul_f32_e32 v68, v28, v68
	v_mul_f32_e32 v69, v28, v69
	v_mul_f32_e32 v70, v28, v70
	v_mul_f32_e32 v71, v28, v71
	v_mul_f32_e32 v68, v68, v36
	v_mul_f32_e32 v69, v69, v37
	v_mul_f32_e32 v70, v70, v38
	v_mul_f32_e32 v71, v71, v39
	global_store_dwordx4 v[14:15], v[68:71], off offset:-3072 nt
	v_mul_f32_e32 v72, v28, v72
	v_mul_f32_e32 v73, v28, v73
	v_mul_f32_e32 v74, v28, v74
	v_mul_f32_e32 v75, v28, v75
	v_mul_f32_e32 v72, v72, v40
	v_mul_f32_e32 v73, v73, v41
	v_mul_f32_e32 v74, v74, v42
	v_mul_f32_e32 v75, v75, v43
	global_store_dwordx4 v[14:15], v[72:75], off offset:-2048 nt
	v_mul_f32_e32 v76, v28, v76
	v_mul_f32_e32 v77, v28, v77
	v_mul_f32_e32 v78, v28, v78
	v_mul_f32_e32 v79, v28, v79
	v_mul_f32_e32 v76, v76, v44
	v_mul_f32_e32 v77, v77, v45
	v_mul_f32_e32 v78, v78, v46
	v_mul_f32_e32 v79, v79, v47
	global_store_dwordx4 v[14:15], v[76:79], off offset:-1024 nt
	v_mul_f32_e32 v80, v28, v80
	v_mul_f32_e32 v81, v28, v81
	v_mul_f32_e32 v82, v28, v82
	v_mul_f32_e32 v83, v28, v83
	v_mul_f32_e32 v80, v80, v48
	v_mul_f32_e32 v81, v81, v49
	v_mul_f32_e32 v82, v82, v50
	v_mul_f32_e32 v83, v83, v51
	global_store_dwordx4 v[14:15], v[80:83], off offset:0 nt
	v_mul_f32_e32 v84, v28, v84
	v_mul_f32_e32 v85, v28, v85
	v_mul_f32_e32 v86, v28, v86
	v_mul_f32_e32 v87, v28, v87
	v_mul_f32_e32 v84, v84, v52
	v_mul_f32_e32 v85, v85, v53
	v_mul_f32_e32 v86, v86, v54
	v_mul_f32_e32 v87, v87, v55
	global_store_dwordx4 v[14:15], v[84:87], off offset:1024 nt
	v_mul_f32_e32 v88, v28, v88
	v_mul_f32_e32 v89, v28, v89
	v_mul_f32_e32 v90, v28, v90
	v_mul_f32_e32 v91, v28, v91
	v_mul_f32_e32 v88, v88, v56
	v_mul_f32_e32 v89, v89, v57
	v_mul_f32_e32 v90, v90, v58
	v_mul_f32_e32 v91, v91, v59
	global_store_dwordx4 v[14:15], v[88:91], off offset:2048 nt
	v_mul_f32_e32 v92, v28, v92
	v_mul_f32_e32 v93, v28, v93
	v_mul_f32_e32 v94, v28, v94
	v_mul_f32_e32 v95, v28, v95
	v_mul_f32_e32 v92, v92, v60
	v_mul_f32_e32 v93, v93, v61
	v_mul_f32_e32 v94, v94, v62
	v_mul_f32_e32 v95, v95, v63
	global_store_dwordx4 v[14:15], v[92:95], off offset:3072 nt
	s_endpgm
.Lp8_tail_b:
	s_waitcnt vmcnt(0)
	v_fmamk_f32 v30, v30, 0x3a000000, v0
	v_rsq_f32_e32 v30, v30
	s_nop 0
	v_mul_f32_e32 v96, v30, v96
	v_mul_f32_e32 v97, v30, v97
	v_mul_f32_e32 v98, v30, v98
	v_mul_f32_e32 v99, v30, v99
	v_mul_f32_e32 v96, v96, v32
	v_mul_f32_e32 v97, v97, v33
	v_mul_f32_e32 v98, v98, v34
	v_mul_f32_e32 v99, v99, v35
	global_store_dwordx4 v[16:17], v[96:99], off offset:-4096 nt
	v_mul_f32_e32 v100, v30, v100
	v_mul_f32_e32 v101, v30, v101
	v_mul_f32_e32 v102, v30, v102
	v_mul_f32_e32 v103, v30, v103
	v_mul_f32_e32 v100, v100, v36
	v_mul_f32_e32 v101, v101, v37
	v_mul_f32_e32 v102, v102, v38
	v_mul_f32_e32 v103, v103, v39
	global_store_dwordx4 v[16:17], v[100:103], off offset:-3072 nt
	v_mul_f32_e32 v104, v30, v104
	v_mul_f32_e32 v105, v30, v105
	v_mul_f32_e32 v106, v30, v106
	v_mul_f32_e32 v107, v30, v107
	v_mul_f32_e32 v104, v104, v40
	v_mul_f32_e32 v105, v105, v41
	v_mul_f32_e32 v106, v106, v42
	v_mul_f32_e32 v107, v107, v43
	global_store_dwordx4 v[16:17], v[104:107], off offset:-2048 nt
	v_mul_f32_e32 v108, v30, v108
	v_mul_f32_e32 v109, v30, v109
	v_mul_f32_e32 v110, v30, v110
	v_mul_f32_e32 v111, v30, v111
	v_mul_f32_e32 v108, v108, v44
	v_mul_f32_e32 v109, v109, v45
	v_mul_f32_e32 v110, v110, v46
	v_mul_f32_e32 v111, v111, v47
	global_store_dwordx4 v[16:17], v[108:111], off offset:-1024 nt
	v_mul_f32_e32 v112, v30, v112
	v_mul_f32_e32 v113, v30, v113
	v_mul_f32_e32 v114, v30, v114
	v_mul_f32_e32 v115, v30, v115
	v_mul_f32_e32 v112, v112, v48
	v_mul_f32_e32 v113, v113, v49
	v_mul_f32_e32 v114, v114, v50
	v_mul_f32_e32 v115, v115, v51
	global_store_dwordx4 v[16:17], v[112:115], off offset:0 nt
	v_mul_f32_e32 v116, v30, v116
	v_mul_f32_e32 v117, v30, v117
	v_mul_f32_e32 v118, v30, v118
	v_mul_f32_e32 v119, v30, v119
	v_mul_f32_e32 v116, v116, v52
	v_mul_f32_e32 v117, v117, v53
	v_mul_f32_e32 v118, v118, v54
	v_mul_f32_e32 v119, v119, v55
	global_store_dwordx4 v[16:17], v[116:119], off offset:1024 nt
	v_mul_f32_e32 v120, v30, v120
	v_mul_f32_e32 v121, v30, v121
	v_mul_f32_e32 v122, v30, v122
	v_mul_f32_e32 v123, v30, v123
	v_mul_f32_e32 v120, v120, v56
	v_mul_f32_e32 v121, v121, v57
	v_mul_f32_e32 v122, v122, v58
	v_mul_f32_e32 v123, v123, v59
	global_store_dwordx4 v[16:17], v[120:123], off offset:2048 nt
	v_mul_f32_e32 v124, v30, v124
	v_mul_f32_e32 v125, v30, v125
	v_mul_f32_e32 v126, v30, v126
	v_mul_f32_e32 v127, v30, v127
	v_mul_f32_e32 v124, v124, v60
	v_mul_f32_e32 v125, v125, v61
	v_mul_f32_e32 v126, v126, v62
	v_mul_f32_e32 v127, v127, v63
	global_store_dwordx4 v[16:17], v[124:127], off offset:3072 nt
